# F epilogue: both column halves' gate vectors loaded up front (removes a load round trip plus store drain per tile); on top of v54
# speedup vs baseline: 1.0043x; 1.0043x over previous
.LBB0_842:
	s_cmp_gt_u32 s47, 31
	s_cselect_b32 s26, 0x6000, 0
	s_add_u32 s26, s58, s26
	s_addc_u32 s27, s59, 0
	s_add_u32 s26, s26, 0x4000
	v_lshl_or_b32 v132, s48, 8, v150
	s_addc_u32 s27, s27, 0
	v_lshl_add_u64 v[140:141], v[132:133], 2, s[26:27]
	global_load_dwordx4 v[154:157], v[140:141], off
	global_load_dwordx4 v[158:161], v[140:141], off offset:16
	global_load_dwordx4 v[184:187], v[140:141], off offset:512
	global_load_dwordx4 v[188:191], v[140:141], off offset:528
	v_lshl_add_u32 v140, s47, 8, v148
	v_ashrrev_i32_e32 v141, 31, v140
	v_or_b32_e32 v142, 16, v140
	v_or_b32_e32 v144, 32, v140
	v_or_b32_e32 v162, 48, v140
	v_lshlrev_b64 v[140:141], 12, v[140:141]
	v_ashrrev_i32_e32 v143, 31, v142
	v_ashrrev_i32_e32 v145, 31, v144
	v_ashrrev_i32_e32 v163, 31, v162
	v_lshlrev_b64 v[146:147], 1, v[132:133]
	v_lshl_add_u64 v[140:141], s[6:7], 0, v[140:141]
	v_lshlrev_b64 v[142:143], 12, v[142:143]
	v_lshlrev_b64 v[144:145], 12, v[144:145]
	v_lshlrev_b64 v[162:163], 12, v[162:163]
	v_lshl_add_u64 v[140:141], v[140:141], 0, v[146:147]
	v_lshl_add_u64 v[142:143], s[6:7], 0, v[142:143]
	v_lshl_add_u64 v[144:145], s[6:7], 0, v[144:145]
	v_lshl_add_u64 v[162:163], s[6:7], 0, v[162:163]
	v_lshl_add_u64 v[142:143], v[142:143], 0, v[146:147]
	v_lshl_add_u64 v[144:145], v[144:145], 0, v[146:147]
	v_lshl_add_u64 v[146:147], v[162:163], 0, v[146:147]
	v_add_co_u32_e32 v162, vcc, s43, v140
	v_or_b32_e32 v132, 0x80, v132
	s_nop 0
	v_addc_co_u32_e32 v163, vcc, 0, v141, vcc
	s_waitcnt vmcnt(2)
	v_pk_mul_f32 v[126:127], v[126:127], v[156:157]
	v_pk_mul_f32 v[124:125], v[124:125], v[154:155]
	v_pk_mul_f32 v[122:123], v[122:123], v[160:161]
	v_pk_mul_f32 v[120:121], v[120:121], v[158:159]
	v_pk_mul_f32 v[118:119], v[118:119], v[156:157]
	v_pk_mul_f32 v[116:117], v[116:117], v[154:155]
	v_pk_mul_f32 v[114:115], v[114:115], v[160:161]
	v_pk_mul_f32 v[112:113], v[112:113], v[158:159]
	v_pk_mul_f32 v[110:111], v[110:111], v[156:157]
	v_pk_mul_f32 v[108:109], v[108:109], v[154:155]
	v_pk_mul_f32 v[106:107], v[106:107], v[160:161]
	v_pk_mul_f32 v[104:105], v[104:105], v[158:159]
	v_pk_mul_f32 v[102:103], v[102:103], v[156:157]
	v_pk_mul_f32 v[100:101], v[100:101], v[154:155]
	v_pk_mul_f32 v[98:99], v[98:99], v[160:161]
	v_pk_mul_f32 v[96:97], v[96:97], v[158:159]
	v_pk_mul_f32 v[164:165], v[94:95], v[156:157]
	v_pk_mul_f32 v[166:167], v[92:93], v[154:155]
	v_pk_mul_f32 v[168:169], v[90:91], v[160:161]
	v_pk_mul_f32 v[170:171], v[88:89], v[158:159]
	v_pk_mul_f32 v[176:177], v[82:83], v[160:161]
	v_pk_mul_f32 v[178:179], v[80:81], v[158:159]
	v_cvt_pk_bf16_f32 v80, v124, v125
	v_cvt_pk_bf16_f32 v81, v126, v127
	v_cvt_pk_bf16_f32 v82, v120, v121
	v_cvt_pk_bf16_f32 v83, v122, v123
	v_pk_mul_f32 v[172:173], v[86:87], v[156:157]
	v_pk_mul_f32 v[174:175], v[84:85], v[154:155]
	v_cvt_pk_bf16_f32 v84, v116, v117
	v_cvt_pk_bf16_f32 v85, v118, v119
	v_cvt_pk_bf16_f32 v86, v112, v113
	v_cvt_pk_bf16_f32 v87, v114, v115
	v_cvt_pk_bf16_f32 v88, v108, v109
	v_cvt_pk_bf16_f32 v89, v110, v111
	v_cvt_pk_bf16_f32 v90, v104, v105
	v_cvt_pk_bf16_f32 v91, v106, v107
	v_cvt_pk_bf16_f32 v92, v100, v101
	v_cvt_pk_bf16_f32 v93, v102, v103
	v_cvt_pk_bf16_f32 v94, v96, v97
	v_cvt_pk_bf16_f32 v95, v98, v99
	v_cvt_pk_bf16_f32 v96, v166, v167
	v_cvt_pk_bf16_f32 v97, v164, v165
	v_cvt_pk_bf16_f32 v98, v170, v171
	v_cvt_pk_bf16_f32 v99, v168, v169
	global_store_dwordx4 v[140:141], v[80:83], off
	global_store_dwordx4 v[142:143], v[84:87], off
	global_store_dwordx4 v[144:145], v[88:91], off
	global_store_dwordx4 v[146:147], v[92:95], off
	global_store_dwordx4 v[162:163], v[96:99], off
	v_add_co_u32_e32 v80, vcc, s44, v140
	v_cvt_pk_bf16_f32 v100, v174, v175
	v_cvt_pk_bf16_f32 v101, v172, v173
	v_cvt_pk_bf16_f32 v102, v178, v179
	v_cvt_pk_bf16_f32 v103, v176, v177
	v_addc_co_u32_e32 v81, vcc, 0, v141, vcc
	v_pk_mul_f32 v[76:77], v[76:77], v[154:155]
	global_store_dwordx4 v[80:81], v[100:103], off
	v_pk_mul_f32 v[78:79], v[78:79], v[156:157]
	v_pk_mul_f32 v[80:81], v[74:75], v[160:161]
	v_pk_mul_f32 v[74:75], v[72:73], v[158:159]
	v_cvt_pk_bf16_f32 v72, v76, v77
	v_add_co_u32_e32 v76, vcc, s45, v140
	v_cvt_pk_bf16_f32 v73, v78, v79
	v_cvt_pk_bf16_f32 v74, v74, v75
	v_cvt_pk_bf16_f32 v75, v80, v81
	v_addc_co_u32_e32 v77, vcc, 0, v141, vcc
	v_pk_mul_f32 v[60:61], v[60:61], v[154:155]
	global_store_dwordx4 v[76:77], v[72:75], off
	v_pk_mul_f32 v[62:63], v[62:63], v[156:157]
	v_lshl_add_u64 v[76:77], v[140:141], 0, s[22:23]
	v_pk_mul_f32 v[72:73], v[54:55], v[160:161]
	v_pk_mul_f32 v[54:55], v[52:53], v[158:159]
	v_cvt_pk_bf16_f32 v52, v60, v61
	v_add_co_u32_e32 v60, vcc, s46, v140
	v_cvt_pk_bf16_f32 v53, v62, v63
	v_cvt_pk_bf16_f32 v54, v54, v55
	v_cvt_pk_bf16_f32 v55, v72, v73
	v_addc_co_u32_e32 v61, vcc, 0, v141, vcc
	global_store_dwordx4 v[60:61], v[52:55], off
	v_lshl_add_u64 v[60:61], v[132:133], 2, s[26:27]
	s_waitcnt vmcnt(8)
	s_nop 1
	v_mov_b64_e32 v[52:53], v[184:185]
	v_mov_b64_e32 v[54:55], v[186:187]
	v_mov_b64_e32 v[60:61], v[188:189]
	v_mov_b64_e32 v[62:63], v[190:191]
	v_lshl_add_u64 v[72:73], v[140:141], 0, s[10:11]
	v_lshl_add_u64 v[74:75], v[140:141], 0, s[20:21]
	v_lshl_add_u64 v[78:79], v[140:141], 0, s[24:25]
	s_andn2_b64 vcc, exec, s[0:1]
	s_mov_b64 s[0:1], -1
	s_nop 0
	v_pk_mul_f32 v[70:71], v[70:71], v[54:55]
	v_pk_mul_f32 v[68:69], v[68:69], v[52:53]
	s_nop 0
	v_pk_mul_f32 v[66:67], v[66:67], v[62:63]
	v_pk_mul_f32 v[64:65], v[64:65], v[60:61]
	v_pk_mul_f32 v[58:59], v[58:59], v[54:55]
	v_pk_mul_f32 v[56:57], v[56:57], v[52:53]
	v_pk_mul_f32 v[50:51], v[50:51], v[62:63]
	v_pk_mul_f32 v[48:49], v[48:49], v[60:61]
	v_pk_mul_f32 v[46:47], v[46:47], v[54:55]
	v_pk_mul_f32 v[44:45], v[44:45], v[52:53]
	v_pk_mul_f32 v[42:43], v[42:43], v[62:63]
	v_pk_mul_f32 v[40:41], v[40:41], v[60:61]
	v_pk_mul_f32 v[38:39], v[38:39], v[54:55]
	v_pk_mul_f32 v[36:37], v[36:37], v[52:53]
	v_pk_mul_f32 v[80:81], v[34:35], v[62:63]
	v_pk_mul_f32 v[82:83], v[32:33], v[60:61]
	v_pk_mul_f32 v[84:85], v[30:31], v[54:55]
	v_pk_mul_f32 v[86:87], v[28:29], v[52:53]
	v_pk_mul_f32 v[88:89], v[26:27], v[62:63]
	v_pk_mul_f32 v[90:91], v[24:25], v[60:61]
	v_pk_mul_f32 v[92:93], v[22:23], v[54:55]
	v_cvt_pk_bf16_f32 v22, v68, v69
	v_cvt_pk_bf16_f32 v23, v70, v71
	v_cvt_pk_bf16_f32 v24, v64, v65
	v_cvt_pk_bf16_f32 v25, v66, v67
	v_cvt_pk_bf16_f32 v26, v56, v57
	v_cvt_pk_bf16_f32 v27, v58, v59
	v_cvt_pk_bf16_f32 v28, v48, v49
	v_cvt_pk_bf16_f32 v29, v50, v51
	v_cvt_pk_bf16_f32 v30, v44, v45
	v_cvt_pk_bf16_f32 v31, v46, v47
	v_cvt_pk_bf16_f32 v32, v40, v41
	v_cvt_pk_bf16_f32 v33, v42, v43
	v_cvt_pk_bf16_f32 v34, v36, v37
	v_cvt_pk_bf16_f32 v35, v38, v39
	v_cvt_pk_bf16_f32 v36, v82, v83
	v_cvt_pk_bf16_f32 v37, v80, v81
	v_cvt_pk_bf16_f32 v38, v86, v87
	v_cvt_pk_bf16_f32 v39, v84, v85
	v_cvt_pk_bf16_f32 v40, v90, v91
	v_cvt_pk_bf16_f32 v41, v88, v89
	global_store_dwordx4 v[140:141], v[22:25], off offset:256
	global_store_dwordx4 v[142:143], v[26:29], off offset:256
	global_store_dwordx4 v[144:145], v[30:33], off offset:256
	global_store_dwordx4 v[146:147], v[34:37], off offset:256
	global_store_dwordx4 v[72:73], v[38:41], off offset:256
	v_pk_mul_f32 v[20:21], v[20:21], v[52:53]
	v_pk_mul_f32 v[22:23], v[18:19], v[62:63]
	v_pk_mul_f32 v[18:19], v[16:17], v[60:61]
	v_cvt_pk_bf16_f32 v16, v20, v21
	v_cvt_pk_bf16_f32 v17, v92, v93
	v_cvt_pk_bf16_f32 v18, v18, v19
	v_cvt_pk_bf16_f32 v19, v22, v23
	global_store_dwordx4 v[74:75], v[16:19], off offset:256
	v_pk_mul_f32 v[14:15], v[14:15], v[54:55]
	v_pk_mul_f32 v[12:13], v[12:13], v[52:53]
	v_pk_mul_f32 v[16:17], v[10:11], v[62:63]
	v_pk_mul_f32 v[10:11], v[8:9], v[60:61]
	v_cvt_pk_bf16_f32 v8, v12, v13
	v_cvt_pk_bf16_f32 v9, v14, v15
	v_cvt_pk_bf16_f32 v10, v10, v11
	v_cvt_pk_bf16_f32 v11, v16, v17
	global_store_dwordx4 v[76:77], v[8:11], off offset:256
	v_pk_mul_f32 v[6:7], v[6:7], v[54:55]
	v_pk_mul_f32 v[4:5], v[4:5], v[52:53]
	v_pk_mul_f32 v[8:9], v[2:3], v[62:63]
	v_pk_mul_f32 v[2:3], v[0:1], v[60:61]
	v_cvt_pk_bf16_f32 v0, v4, v5
	v_cvt_pk_bf16_f32 v1, v6, v7
	v_cvt_pk_bf16_f32 v2, v2, v3
	v_cvt_pk_bf16_f32 v3, v8, v9
	global_store_dwordx4 v[78:79], v[0:3], off offset:256
	s_cbranch_vccnz .LBB0_837
	s_andn2_b64 vcc, exec, s[14:15]
	s_cbranch_vccnz .LBB0_836
	s_barrier
	s_branch .LBB0_836
	s_nop 0
	s_nop 0
	s_nop 0
	s_nop 0
	s_nop 0
	s_nop 0
	s_nop 0
	s_nop 0
	s_nop 0
	s_nop 0
	s_nop 0
	s_nop 0
	s_nop 0
	s_nop 0
	s_nop 0
	s_nop 0
	s_nop 0
	s_nop 0
	s_nop 0
	s_nop 0
	s_nop 0
	s_nop 0
	s_nop 0
	s_nop 0
	s_nop 0
	s_nop 0
	s_nop 0
	s_nop 0
	s_nop 0
	s_nop 0
	s_nop 0
	s_nop 0
	s_nop 0
	s_nop 0
	s_nop 0
	s_nop 0
	s_nop 0
	s_nop 0
	s_nop 0
	s_nop 0
	s_nop 0
	s_nop 0
	s_nop 0
	s_nop 0
	s_nop 0
	s_nop 0
	s_nop 0
	s_nop 0
	s_nop 0
	s_nop 0
	s_nop 0
	s_nop 0
	s_nop 0
	s_nop 0
	s_nop 0
	s_nop 0
	s_nop 0
	s_nop 0
	s_nop 0
